# output-projection epilogue hand-written: eg/eb/row stats loaded once, x tiles kept in flight in all free register tiles with counted vmcnt waits (compiled version was 32 dependent load->drain->store s
# speedup vs baseline: 1.0169x; 1.0019x over previous
.LBB0_688:
	v_readlane_b32 s82, v254, 52
	s_andn2_b64 vcc, exec, s[38:39]
	s_mov_b64 s[38:39], -1
	v_readlane_b32 s83, v254, 53
	v_lshl_add_u32 v146, s75, 8, v148
	v_lshlrev_b32_e32 v208, 3, v146
	v_lshl_or_b32 v209, s74, 8, v150
	v_lshlrev_b32_e32 v209, 2, v209
	v_lshl_add_u32 v201, v146, 12, v209
	global_load_dwordx2 v[184:185], v208, s[6:7]
	global_load_dwordx2 v[186:187], v208, s[6:7] offset:128
	global_load_dwordx2 v[188:189], v208, s[6:7] offset:256
	global_load_dwordx2 v[190:191], v208, s[6:7] offset:384
	global_load_dwordx2 v[192:193], v208, s[6:7] offset:1024
	global_load_dwordx2 v[194:195], v208, s[6:7] offset:1152
	global_load_dwordx2 v[196:197], v208, s[6:7] offset:1280
	global_load_dwordx2 v[198:199], v208, s[6:7] offset:1408
	global_load_dwordx4 v[152:155], v209, s[40:41]
	global_load_dwordx4 v[156:159], v209, s[40:41] offset:16
	global_load_dwordx4 v[160:163], v209, s[40:41] offset:512
	global_load_dwordx4 v[164:167], v209, s[40:41] offset:528
	global_load_dwordx4 v[168:171], v209, s[42:43]
	global_load_dwordx4 v[172:175], v209, s[42:43] offset:16
	global_load_dwordx4 v[176:179], v209, s[42:43] offset:512
	global_load_dwordx4 v[180:183], v209, s[42:43] offset:528
	global_load_dwordx4 v[140:143], v201, s[0:1]
	global_load_dwordx4 v[144:147], v201, s[0:1] offset:16
	global_load_dwordx4 v[204:207], v201, s[0:1] offset:512
	global_load_dwordx4 v[208:211], v201, s[0:1] offset:528
	s_waitcnt vmcnt(3)
	v_sub_f32_e32 v140, v140, v184
	v_sub_f32_e32 v141, v141, v184
	v_sub_f32_e32 v142, v142, v184
	v_sub_f32_e32 v143, v143, v184
	v_mul_f32_e32 v140, v185, v140
	v_mul_f32_e32 v141, v185, v141
	v_mul_f32_e32 v142, v185, v142
	v_mul_f32_e32 v143, v185, v143
	s_waitcnt vmcnt(4)
	v_fma_f32 v140, v140, v152, v168
	v_fma_f32 v141, v141, v153, v169
	v_fma_f32 v142, v142, v154, v170
	v_fma_f32 v143, v143, v155, v171
	v_fmac_f32_e32 v128, s30, v140
	v_fmac_f32_e32 v129, s30, v141
	v_fmac_f32_e32 v130, s30, v142
	v_fmac_f32_e32 v131, s30, v143
	global_store_dwordx4 v201, v[128:131], s[8:9]
	v_add_u32_e32 v200, 0x10000, v201
	global_load_dwordx4 v[140:143], v200, s[0:1]
	s_waitcnt vmcnt(4)
	v_sub_f32_e32 v144, v144, v184
	v_sub_f32_e32 v145, v145, v184
	v_sub_f32_e32 v146, v146, v184
	v_sub_f32_e32 v147, v147, v184
	v_mul_f32_e32 v144, v185, v144
	v_mul_f32_e32 v145, v185, v145
	v_mul_f32_e32 v146, v185, v146
	v_mul_f32_e32 v147, v185, v147
	v_fma_f32 v144, v144, v156, v172
	v_fma_f32 v145, v145, v157, v173
	v_fma_f32 v146, v146, v158, v174
	v_fma_f32 v147, v147, v159, v175
	v_fmac_f32_e32 v124, s30, v144
	v_fmac_f32_e32 v125, s30, v145
	v_fmac_f32_e32 v126, s30, v146
	v_fmac_f32_e32 v127, s30, v147
	global_store_dwordx4 v201, v[124:127], s[8:9] offset:16
	v_add_u32_e32 v200, 0x10000, v201
	global_load_dwordx4 v[144:147], v200, s[0:1] offset:16
	s_waitcnt vmcnt(5)
	v_sub_f32_e32 v204, v204, v184
	v_sub_f32_e32 v205, v205, v184
	v_sub_f32_e32 v206, v206, v184
	v_sub_f32_e32 v207, v207, v184
	v_mul_f32_e32 v204, v185, v204
	v_mul_f32_e32 v205, v185, v205
	v_mul_f32_e32 v206, v185, v206
	v_mul_f32_e32 v207, v185, v207
	v_fma_f32 v204, v204, v160, v176
	v_fma_f32 v205, v205, v161, v177
	v_fma_f32 v206, v206, v162, v178
	v_fma_f32 v207, v207, v163, v179
	v_fmac_f32_e32 v120, s30, v204
	v_fmac_f32_e32 v121, s30, v205
	v_fmac_f32_e32 v122, s30, v206
	v_fmac_f32_e32 v123, s30, v207
	global_store_dwordx4 v201, v[120:123], s[8:9] offset:512
	v_add_u32_e32 v200, 0x10000, v201
	global_load_dwordx4 v[204:207], v200, s[0:1] offset:512
	s_waitcnt vmcnt(6)
	v_sub_f32_e32 v208, v208, v184
	v_sub_f32_e32 v209, v209, v184
	v_sub_f32_e32 v210, v210, v184
	v_sub_f32_e32 v211, v211, v184
	v_mul_f32_e32 v208, v185, v208
	v_mul_f32_e32 v209, v185, v209
	v_mul_f32_e32 v210, v185, v210
	v_mul_f32_e32 v211, v185, v211
	v_fma_f32 v208, v208, v164, v180
	v_fma_f32 v209, v209, v165, v181
	v_fma_f32 v210, v210, v166, v182
	v_fma_f32 v211, v211, v167, v183
	v_fmac_f32_e32 v116, s30, v208
	v_fmac_f32_e32 v117, s30, v209
	v_fmac_f32_e32 v118, s30, v210
	v_fmac_f32_e32 v119, s30, v211
	global_store_dwordx4 v201, v[116:119], s[8:9] offset:528
	s_nop 1
	v_add_u32_e32 v200, 0x10000, v201
	global_load_dwordx4 v[208:211], v200, s[0:1] offset:528
	v_add_u32_e32 v200, 0x20000, v201
	global_load_dwordx4 v[128:131], v200, s[0:1]
	v_add_u32_e32 v200, 0x20000, v201
	global_load_dwordx4 v[124:127], v200, s[0:1] offset:16
	v_add_u32_e32 v200, 0x20000, v201
	global_load_dwordx4 v[120:123], v200, s[0:1] offset:512
	v_add_u32_e32 v200, 0x20000, v201
	global_load_dwordx4 v[116:119], v200, s[0:1] offset:528
	s_waitcnt vmcnt(10)
	v_sub_f32_e32 v140, v140, v186
	v_sub_f32_e32 v141, v141, v186
	v_sub_f32_e32 v142, v142, v186
	v_sub_f32_e32 v143, v143, v186
	v_mul_f32_e32 v140, v187, v140
	v_mul_f32_e32 v141, v187, v141
	v_mul_f32_e32 v142, v187, v142
	v_mul_f32_e32 v143, v187, v143
	v_fma_f32 v140, v140, v152, v168
	v_fma_f32 v141, v141, v153, v169
	v_fma_f32 v142, v142, v154, v170
	v_fma_f32 v143, v143, v155, v171
	v_fmac_f32_e32 v112, s30, v140
	v_fmac_f32_e32 v113, s30, v141
	v_fmac_f32_e32 v114, s30, v142
	v_fmac_f32_e32 v115, s30, v143
	v_add_u32_e32 v200, 0x10000, v201
	global_store_dwordx4 v200, v[112:115], s[8:9]
	v_add_u32_e32 v200, 0x30000, v201
	global_load_dwordx4 v[140:143], v200, s[0:1]
	s_waitcnt vmcnt(10)
	v_sub_f32_e32 v144, v144, v186
	v_sub_f32_e32 v145, v145, v186
	v_sub_f32_e32 v146, v146, v186
	v_sub_f32_e32 v147, v147, v186
	v_mul_f32_e32 v144, v187, v144
	v_mul_f32_e32 v145, v187, v145
	v_mul_f32_e32 v146, v187, v146
	v_mul_f32_e32 v147, v187, v147
	v_fma_f32 v144, v144, v156, v172
	v_fma_f32 v145, v145, v157, v173
	v_fma_f32 v146, v146, v158, v174
	v_fma_f32 v147, v147, v159, v175
	v_fmac_f32_e32 v108, s30, v144
	v_fmac_f32_e32 v109, s30, v145
	v_fmac_f32_e32 v110, s30, v146
	v_fmac_f32_e32 v111, s30, v147
	v_add_u32_e32 v200, 0x10000, v201
	global_store_dwordx4 v200, v[108:111], s[8:9] offset:16
	v_add_u32_e32 v200, 0x30000, v201
	global_load_dwordx4 v[144:147], v200, s[0:1] offset:16
	s_waitcnt vmcnt(10)
	v_sub_f32_e32 v204, v204, v186
	v_sub_f32_e32 v205, v205, v186
	v_sub_f32_e32 v206, v206, v186
	v_sub_f32_e32 v207, v207, v186
	v_mul_f32_e32 v204, v187, v204
	v_mul_f32_e32 v205, v187, v205
	v_mul_f32_e32 v206, v187, v206
	v_mul_f32_e32 v207, v187, v207
	v_fma_f32 v204, v204, v160, v176
	v_fma_f32 v205, v205, v161, v177
	v_fma_f32 v206, v206, v162, v178
	v_fma_f32 v207, v207, v163, v179
	v_fmac_f32_e32 v104, s30, v204
	v_fmac_f32_e32 v105, s30, v205
	v_fmac_f32_e32 v106, s30, v206
	v_fmac_f32_e32 v107, s30, v207
	v_add_u32_e32 v200, 0x10000, v201
	global_store_dwordx4 v200, v[104:107], s[8:9] offset:512
	v_add_u32_e32 v200, 0x30000, v201
	global_load_dwordx4 v[204:207], v200, s[0:1] offset:512
	s_waitcnt vmcnt(10)
	v_sub_f32_e32 v208, v208, v186
	v_sub_f32_e32 v209, v209, v186
	v_sub_f32_e32 v210, v210, v186
	v_sub_f32_e32 v211, v211, v186
	v_mul_f32_e32 v208, v187, v208
	v_mul_f32_e32 v209, v187, v209
	v_mul_f32_e32 v210, v187, v210
	v_mul_f32_e32 v211, v187, v211
	v_fma_f32 v208, v208, v164, v180
	v_fma_f32 v209, v209, v165, v181
	v_fma_f32 v210, v210, v166, v182
	v_fma_f32 v211, v211, v167, v183
	v_fmac_f32_e32 v100, s30, v208
	v_fmac_f32_e32 v101, s30, v209
	v_fmac_f32_e32 v102, s30, v210
	v_fmac_f32_e32 v103, s30, v211
	v_add_u32_e32 v200, 0x10000, v201
	global_store_dwordx4 v200, v[100:103], s[8:9] offset:528
	s_nop 1
	v_add_u32_e32 v200, 0x30000, v201
	global_load_dwordx4 v[208:211], v200, s[0:1] offset:528
	v_add_u32_e32 v200, 0x80000, v201
	global_load_dwordx4 v[112:115], v200, s[0:1]
	v_add_u32_e32 v200, 0x80000, v201
	global_load_dwordx4 v[108:111], v200, s[0:1] offset:16
	v_add_u32_e32 v200, 0x80000, v201
	global_load_dwordx4 v[104:107], v200, s[0:1] offset:512
	v_add_u32_e32 v200, 0x80000, v201
	global_load_dwordx4 v[100:103], v200, s[0:1] offset:528
	s_waitcnt vmcnt(15)
	v_sub_f32_e32 v128, v128, v188
	v_sub_f32_e32 v129, v129, v188
	v_sub_f32_e32 v130, v130, v188
	v_sub_f32_e32 v131, v131, v188
	v_mul_f32_e32 v128, v189, v128
	v_mul_f32_e32 v129, v189, v129
	v_mul_f32_e32 v130, v189, v130
	v_mul_f32_e32 v131, v189, v131
	v_fma_f32 v128, v128, v152, v168
	v_fma_f32 v129, v129, v153, v169
	v_fma_f32 v130, v130, v154, v170
	v_fma_f32 v131, v131, v155, v171
	v_fmac_f32_e32 v96, s30, v128
	v_fmac_f32_e32 v97, s30, v129
	v_fmac_f32_e32 v98, s30, v130
	v_fmac_f32_e32 v99, s30, v131
	v_add_u32_e32 v200, 0x20000, v201
	global_store_dwordx4 v200, v[96:99], s[8:9]
	v_add_u32_e32 v200, 0x90000, v201
	global_load_dwordx4 v[128:131], v200, s[0:1]
	s_waitcnt vmcnt(16)
	v_sub_f32_e32 v124, v124, v188
	v_sub_f32_e32 v125, v125, v188
	v_sub_f32_e32 v126, v126, v188
	v_sub_f32_e32 v127, v127, v188
	v_mul_f32_e32 v124, v189, v124
	v_mul_f32_e32 v125, v189, v125
	v_mul_f32_e32 v126, v189, v126
	v_mul_f32_e32 v127, v189, v127
	v_fma_f32 v124, v124, v156, v172
	v_fma_f32 v125, v125, v157, v173
	v_fma_f32 v126, v126, v158, v174
	v_fma_f32 v127, v127, v159, v175
	v_fmac_f32_e32 v92, s30, v124
	v_fmac_f32_e32 v93, s30, v125
	v_fmac_f32_e32 v94, s30, v126
	v_fmac_f32_e32 v95, s30, v127
	v_add_u32_e32 v200, 0x20000, v201
	global_store_dwordx4 v200, v[92:95], s[8:9] offset:16
	v_add_u32_e32 v200, 0x90000, v201
	global_load_dwordx4 v[124:127], v200, s[0:1] offset:16
	s_waitcnt vmcnt(17)
	v_sub_f32_e32 v120, v120, v188
	v_sub_f32_e32 v121, v121, v188
	v_sub_f32_e32 v122, v122, v188
	v_sub_f32_e32 v123, v123, v188
	v_mul_f32_e32 v120, v189, v120
	v_mul_f32_e32 v121, v189, v121
	v_mul_f32_e32 v122, v189, v122
	v_mul_f32_e32 v123, v189, v123
	v_fma_f32 v120, v120, v160, v176
	v_fma_f32 v121, v121, v161, v177
	v_fma_f32 v122, v122, v162, v178
	v_fma_f32 v123, v123, v163, v179
	v_fmac_f32_e32 v88, s30, v120
	v_fmac_f32_e32 v89, s30, v121
	v_fmac_f32_e32 v90, s30, v122
	v_fmac_f32_e32 v91, s30, v123
	v_add_u32_e32 v200, 0x20000, v201
	global_store_dwordx4 v200, v[88:91], s[8:9] offset:512
	v_add_u32_e32 v200, 0x90000, v201
	global_load_dwordx4 v[120:123], v200, s[0:1] offset:512
	s_waitcnt vmcnt(18)
	v_sub_f32_e32 v116, v116, v188
	v_sub_f32_e32 v117, v117, v188
	v_sub_f32_e32 v118, v118, v188
	v_sub_f32_e32 v119, v119, v188
	v_mul_f32_e32 v116, v189, v116
	v_mul_f32_e32 v117, v189, v117
	v_mul_f32_e32 v118, v189, v118
	v_mul_f32_e32 v119, v189, v119
	v_fma_f32 v116, v116, v164, v180
	v_fma_f32 v117, v117, v165, v181
	v_fma_f32 v118, v118, v166, v182
	v_fma_f32 v119, v119, v167, v183
	v_fmac_f32_e32 v84, s30, v116
	v_fmac_f32_e32 v85, s30, v117
	v_fmac_f32_e32 v86, s30, v118
	v_fmac_f32_e32 v87, s30, v119
	v_add_u32_e32 v200, 0x20000, v201
	global_store_dwordx4 v200, v[84:87], s[8:9] offset:528
	s_nop 1
	v_add_u32_e32 v200, 0x90000, v201
	global_load_dwordx4 v[116:119], v200, s[0:1] offset:528
	v_add_u32_e32 v200, 0xa0000, v201
	global_load_dwordx4 v[96:99], v200, s[0:1]
	v_add_u32_e32 v200, 0xa0000, v201
	global_load_dwordx4 v[92:95], v200, s[0:1] offset:16
	v_add_u32_e32 v200, 0xa0000, v201
	global_load_dwordx4 v[88:91], v200, s[0:1] offset:512
	v_add_u32_e32 v200, 0xa0000, v201
	global_load_dwordx4 v[84:87], v200, s[0:1] offset:528
	s_waitcnt vmcnt(22)
	v_sub_f32_e32 v140, v140, v190
	v_sub_f32_e32 v141, v141, v190
	v_sub_f32_e32 v142, v142, v190
	v_sub_f32_e32 v143, v143, v190
	v_mul_f32_e32 v140, v191, v140
	v_mul_f32_e32 v141, v191, v141
	v_mul_f32_e32 v142, v191, v142
	v_mul_f32_e32 v143, v191, v143
	v_fma_f32 v140, v140, v152, v168
	v_fma_f32 v141, v141, v153, v169
	v_fma_f32 v142, v142, v154, v170
	v_fma_f32 v143, v143, v155, v171
	v_fmac_f32_e32 v80, s30, v140
	v_fmac_f32_e32 v81, s30, v141
	v_fmac_f32_e32 v82, s30, v142
	v_fmac_f32_e32 v83, s30, v143
	v_add_u32_e32 v200, 0x30000, v201
	global_store_dwordx4 v200, v[80:83], s[8:9]
	v_add_u32_e32 v200, 0xb0000, v201
	global_load_dwordx4 v[140:143], v200, s[0:1]
	s_waitcnt vmcnt(22)
	v_sub_f32_e32 v144, v144, v190
	v_sub_f32_e32 v145, v145, v190
	v_sub_f32_e32 v146, v146, v190
	v_sub_f32_e32 v147, v147, v190
	v_mul_f32_e32 v144, v191, v144
	v_mul_f32_e32 v145, v191, v145
	v_mul_f32_e32 v146, v191, v146
	v_mul_f32_e32 v147, v191, v147
	v_fma_f32 v144, v144, v156, v172
	v_fma_f32 v145, v145, v157, v173
	v_fma_f32 v146, v146, v158, v174
	v_fma_f32 v147, v147, v159, v175
	v_fmac_f32_e32 v76, s30, v144
	v_fmac_f32_e32 v77, s30, v145
	v_fmac_f32_e32 v78, s30, v146
	v_fmac_f32_e32 v79, s30, v147
	v_add_u32_e32 v200, 0x30000, v201
	global_store_dwordx4 v200, v[76:79], s[8:9] offset:16
	v_add_u32_e32 v200, 0xb0000, v201
	global_load_dwordx4 v[144:147], v200, s[0:1] offset:16
	s_waitcnt vmcnt(22)
	v_sub_f32_e32 v204, v204, v190
	v_sub_f32_e32 v205, v205, v190
	v_sub_f32_e32 v206, v206, v190
	v_sub_f32_e32 v207, v207, v190
	v_mul_f32_e32 v204, v191, v204
	v_mul_f32_e32 v205, v191, v205
	v_mul_f32_e32 v206, v191, v206
	v_mul_f32_e32 v207, v191, v207
	v_fma_f32 v204, v204, v160, v176
	v_fma_f32 v205, v205, v161, v177
	v_fma_f32 v206, v206, v162, v178
	v_fma_f32 v207, v207, v163, v179
	v_fmac_f32_e32 v72, s30, v204
	v_fmac_f32_e32 v73, s30, v205
	v_fmac_f32_e32 v74, s30, v206
	v_fmac_f32_e32 v75, s30, v207
	v_add_u32_e32 v200, 0x30000, v201
	global_store_dwordx4 v200, v[72:75], s[8:9] offset:512
	v_add_u32_e32 v200, 0xb0000, v201
	global_load_dwordx4 v[204:207], v200, s[0:1] offset:512
	s_waitcnt vmcnt(22)
	v_sub_f32_e32 v208, v208, v190
	v_sub_f32_e32 v209, v209, v190
	v_sub_f32_e32 v210, v210, v190
	v_sub_f32_e32 v211, v211, v190
	v_mul_f32_e32 v208, v191, v208
	v_mul_f32_e32 v209, v191, v209
	v_mul_f32_e32 v210, v191, v210
	v_mul_f32_e32 v211, v191, v211
	v_fma_f32 v208, v208, v164, v180
	v_fma_f32 v209, v209, v165, v181
	v_fma_f32 v210, v210, v166, v182
	v_fma_f32 v211, v211, v167, v183
	v_fmac_f32_e32 v68, s30, v208
	v_fmac_f32_e32 v69, s30, v209
	v_fmac_f32_e32 v70, s30, v210
	v_fmac_f32_e32 v71, s30, v211
	v_add_u32_e32 v200, 0x30000, v201
	global_store_dwordx4 v200, v[68:71], s[8:9] offset:528
	s_nop 1
	v_add_u32_e32 v200, 0xb0000, v201
	global_load_dwordx4 v[208:211], v200, s[0:1] offset:528
	s_waitcnt vmcnt(23)
	v_sub_f32_e32 v112, v112, v192
	v_sub_f32_e32 v113, v113, v192
	v_sub_f32_e32 v114, v114, v192
	v_sub_f32_e32 v115, v115, v192
	v_mul_f32_e32 v112, v193, v112
	v_mul_f32_e32 v113, v193, v113
	v_mul_f32_e32 v114, v193, v114
	v_mul_f32_e32 v115, v193, v115
	v_fma_f32 v112, v112, v152, v168
	v_fma_f32 v113, v113, v153, v169
	v_fma_f32 v114, v114, v154, v170
	v_fma_f32 v115, v115, v155, v171
	v_fmac_f32_e32 v64, s30, v112
	v_fmac_f32_e32 v65, s30, v113
	v_fmac_f32_e32 v66, s30, v114
	v_fmac_f32_e32 v67, s30, v115
	v_add_u32_e32 v200, 0x80000, v201
	global_store_dwordx4 v200, v[64:67], s[8:9]
	s_waitcnt vmcnt(23)
	v_sub_f32_e32 v108, v108, v192
	v_sub_f32_e32 v109, v109, v192
	v_sub_f32_e32 v110, v110, v192
	v_sub_f32_e32 v111, v111, v192
	v_mul_f32_e32 v108, v193, v108
	v_mul_f32_e32 v109, v193, v109
	v_mul_f32_e32 v110, v193, v110
	v_mul_f32_e32 v111, v193, v111
	v_fma_f32 v108, v108, v156, v172
	v_fma_f32 v109, v109, v157, v173
	v_fma_f32 v110, v110, v158, v174
	v_fma_f32 v111, v111, v159, v175
	v_fmac_f32_e32 v60, s30, v108
	v_fmac_f32_e32 v61, s30, v109
	v_fmac_f32_e32 v62, s30, v110
	v_fmac_f32_e32 v63, s30, v111
	v_add_u32_e32 v200, 0x80000, v201
	global_store_dwordx4 v200, v[60:63], s[8:9] offset:16
	s_waitcnt vmcnt(23)
	v_sub_f32_e32 v104, v104, v192
	v_sub_f32_e32 v105, v105, v192
	v_sub_f32_e32 v106, v106, v192
	v_sub_f32_e32 v107, v107, v192
	v_mul_f32_e32 v104, v193, v104
	v_mul_f32_e32 v105, v193, v105
	v_mul_f32_e32 v106, v193, v106
	v_mul_f32_e32 v107, v193, v107
	v_fma_f32 v104, v104, v160, v176
	v_fma_f32 v105, v105, v161, v177
	v_fma_f32 v106, v106, v162, v178
	v_fma_f32 v107, v107, v163, v179
	v_fmac_f32_e32 v56, s30, v104
	v_fmac_f32_e32 v57, s30, v105
	v_fmac_f32_e32 v58, s30, v106
	v_fmac_f32_e32 v59, s30, v107
	v_add_u32_e32 v200, 0x80000, v201
	global_store_dwordx4 v200, v[56:59], s[8:9] offset:512
	s_waitcnt vmcnt(23)
	v_sub_f32_e32 v100, v100, v192
	v_sub_f32_e32 v101, v101, v192
	v_sub_f32_e32 v102, v102, v192
	v_sub_f32_e32 v103, v103, v192
	v_mul_f32_e32 v100, v193, v100
	v_mul_f32_e32 v101, v193, v101
	v_mul_f32_e32 v102, v193, v102
	v_mul_f32_e32 v103, v193, v103
	v_fma_f32 v100, v100, v164, v180
	v_fma_f32 v101, v101, v165, v181
	v_fma_f32 v102, v102, v166, v182
	v_fma_f32 v103, v103, v167, v183
	v_fmac_f32_e32 v52, s30, v100
	v_fmac_f32_e32 v53, s30, v101
	v_fmac_f32_e32 v54, s30, v102
	v_fmac_f32_e32 v55, s30, v103
	v_add_u32_e32 v200, 0x80000, v201
	global_store_dwordx4 v200, v[52:55], s[8:9] offset:528
	s_nop 1
	s_waitcnt vmcnt(22)
	v_sub_f32_e32 v128, v128, v194
	v_sub_f32_e32 v129, v129, v194
	v_sub_f32_e32 v130, v130, v194
	v_sub_f32_e32 v131, v131, v194
	v_mul_f32_e32 v128, v195, v128
	v_mul_f32_e32 v129, v195, v129
	v_mul_f32_e32 v130, v195, v130
	v_mul_f32_e32 v131, v195, v131
	v_fma_f32 v128, v128, v152, v168
	v_fma_f32 v129, v129, v153, v169
	v_fma_f32 v130, v130, v154, v170
	v_fma_f32 v131, v131, v155, v171
	v_fmac_f32_e32 v48, s30, v128
	v_fmac_f32_e32 v49, s30, v129
	v_fmac_f32_e32 v50, s30, v130
	v_fmac_f32_e32 v51, s30, v131
	v_add_u32_e32 v200, 0x90000, v201
	global_store_dwordx4 v200, v[48:51], s[8:9]
	s_waitcnt vmcnt(21)
	v_sub_f32_e32 v124, v124, v194
	v_sub_f32_e32 v125, v125, v194
	v_sub_f32_e32 v126, v126, v194
	v_sub_f32_e32 v127, v127, v194
	v_mul_f32_e32 v124, v195, v124
	v_mul_f32_e32 v125, v195, v125
	v_mul_f32_e32 v126, v195, v126
	v_mul_f32_e32 v127, v195, v127
	v_fma_f32 v124, v124, v156, v172
	v_fma_f32 v125, v125, v157, v173
	v_fma_f32 v126, v126, v158, v174
	v_fma_f32 v127, v127, v159, v175
	v_fmac_f32_e32 v44, s30, v124
	v_fmac_f32_e32 v45, s30, v125
	v_fmac_f32_e32 v46, s30, v126
	v_fmac_f32_e32 v47, s30, v127
	v_add_u32_e32 v200, 0x90000, v201
	global_store_dwordx4 v200, v[44:47], s[8:9] offset:16
	s_waitcnt vmcnt(20)
	v_sub_f32_e32 v120, v120, v194
	v_sub_f32_e32 v121, v121, v194
	v_sub_f32_e32 v122, v122, v194
	v_sub_f32_e32 v123, v123, v194
	v_mul_f32_e32 v120, v195, v120
	v_mul_f32_e32 v121, v195, v121
	v_mul_f32_e32 v122, v195, v122
	v_mul_f32_e32 v123, v195, v123
	v_fma_f32 v120, v120, v160, v176
	v_fma_f32 v121, v121, v161, v177
	v_fma_f32 v122, v122, v162, v178
	v_fma_f32 v123, v123, v163, v179
	v_fmac_f32_e32 v40, s30, v120
	v_fmac_f32_e32 v41, s30, v121
	v_fmac_f32_e32 v42, s30, v122
	v_fmac_f32_e32 v43, s30, v123
	v_add_u32_e32 v200, 0x90000, v201
	global_store_dwordx4 v200, v[40:43], s[8:9] offset:512
	s_waitcnt vmcnt(19)
	v_sub_f32_e32 v116, v116, v194
	v_sub_f32_e32 v117, v117, v194
	v_sub_f32_e32 v118, v118, v194
	v_sub_f32_e32 v119, v119, v194
	v_mul_f32_e32 v116, v195, v116
	v_mul_f32_e32 v117, v195, v117
	v_mul_f32_e32 v118, v195, v118
	v_mul_f32_e32 v119, v195, v119
	v_fma_f32 v116, v116, v164, v180
	v_fma_f32 v117, v117, v165, v181
	v_fma_f32 v118, v118, v166, v182
	v_fma_f32 v119, v119, v167, v183
	v_fmac_f32_e32 v36, s30, v116
	v_fmac_f32_e32 v37, s30, v117
	v_fmac_f32_e32 v38, s30, v118
	v_fmac_f32_e32 v39, s30, v119
	v_add_u32_e32 v200, 0x90000, v201
	global_store_dwordx4 v200, v[36:39], s[8:9] offset:528
	s_nop 1
	s_waitcnt vmcnt(19)
	v_sub_f32_e32 v96, v96, v196
	v_sub_f32_e32 v97, v97, v196
	v_sub_f32_e32 v98, v98, v196
	v_sub_f32_e32 v99, v99, v196
	v_mul_f32_e32 v96, v197, v96
	v_mul_f32_e32 v97, v197, v97
	v_mul_f32_e32 v98, v197, v98
	v_mul_f32_e32 v99, v197, v99
	v_fma_f32 v96, v96, v152, v168
	v_fma_f32 v97, v97, v153, v169
	v_fma_f32 v98, v98, v154, v170
	v_fma_f32 v99, v99, v155, v171
	v_fmac_f32_e32 v32, s30, v96
	v_fmac_f32_e32 v33, s30, v97
	v_fmac_f32_e32 v34, s30, v98
	v_fmac_f32_e32 v35, s30, v99
	v_add_u32_e32 v200, 0xa0000, v201
	global_store_dwordx4 v200, v[32:35], s[8:9]
	s_waitcnt vmcnt(19)
	v_sub_f32_e32 v92, v92, v196
	v_sub_f32_e32 v93, v93, v196
	v_sub_f32_e32 v94, v94, v196
	v_sub_f32_e32 v95, v95, v196
	v_mul_f32_e32 v92, v197, v92
	v_mul_f32_e32 v93, v197, v93
	v_mul_f32_e32 v94, v197, v94
	v_mul_f32_e32 v95, v197, v95
	v_fma_f32 v92, v92, v156, v172
	v_fma_f32 v93, v93, v157, v173
	v_fma_f32 v94, v94, v158, v174
	v_fma_f32 v95, v95, v159, v175
	v_fmac_f32_e32 v28, s30, v92
	v_fmac_f32_e32 v29, s30, v93
	v_fmac_f32_e32 v30, s30, v94
	v_fmac_f32_e32 v31, s30, v95
	v_add_u32_e32 v200, 0xa0000, v201
	global_store_dwordx4 v200, v[28:31], s[8:9] offset:16
	s_waitcnt vmcnt(19)
	v_sub_f32_e32 v88, v88, v196
	v_sub_f32_e32 v89, v89, v196
	v_sub_f32_e32 v90, v90, v196
	v_sub_f32_e32 v91, v91, v196
	v_mul_f32_e32 v88, v197, v88
	v_mul_f32_e32 v89, v197, v89
	v_mul_f32_e32 v90, v197, v90
	v_mul_f32_e32 v91, v197, v91
	v_fma_f32 v88, v88, v160, v176
	v_fma_f32 v89, v89, v161, v177
	v_fma_f32 v90, v90, v162, v178
	v_fma_f32 v91, v91, v163, v179
	v_fmac_f32_e32 v24, s30, v88
	v_fmac_f32_e32 v25, s30, v89
	v_fmac_f32_e32 v26, s30, v90
	v_fmac_f32_e32 v27, s30, v91
	v_add_u32_e32 v200, 0xa0000, v201
	global_store_dwordx4 v200, v[24:27], s[8:9] offset:512
	s_waitcnt vmcnt(19)
	v_sub_f32_e32 v84, v84, v196
	v_sub_f32_e32 v85, v85, v196
	v_sub_f32_e32 v86, v86, v196
	v_sub_f32_e32 v87, v87, v196
	v_mul_f32_e32 v84, v197, v84
	v_mul_f32_e32 v85, v197, v85
	v_mul_f32_e32 v86, v197, v86
	v_mul_f32_e32 v87, v197, v87
	v_fma_f32 v84, v84, v164, v180
	v_fma_f32 v85, v85, v165, v181
	v_fma_f32 v86, v86, v166, v182
	v_fma_f32 v87, v87, v167, v183
	v_fmac_f32_e32 v20, s30, v84
	v_fmac_f32_e32 v21, s30, v85
	v_fmac_f32_e32 v22, s30, v86
	v_fmac_f32_e32 v23, s30, v87
	v_add_u32_e32 v200, 0xa0000, v201
	global_store_dwordx4 v200, v[20:23], s[8:9] offset:528
	s_nop 1
	s_waitcnt vmcnt(18)
	v_sub_f32_e32 v140, v140, v198
	v_sub_f32_e32 v141, v141, v198
	v_sub_f32_e32 v142, v142, v198
	v_sub_f32_e32 v143, v143, v198
	v_mul_f32_e32 v140, v199, v140
	v_mul_f32_e32 v141, v199, v141
	v_mul_f32_e32 v142, v199, v142
	v_mul_f32_e32 v143, v199, v143
	v_fma_f32 v140, v140, v152, v168
	v_fma_f32 v141, v141, v153, v169
	v_fma_f32 v142, v142, v154, v170
	v_fma_f32 v143, v143, v155, v171
	v_fmac_f32_e32 v16, s30, v140
	v_fmac_f32_e32 v17, s30, v141
	v_fmac_f32_e32 v18, s30, v142
	v_fmac_f32_e32 v19, s30, v143
	v_add_u32_e32 v200, 0xb0000, v201
	global_store_dwordx4 v200, v[16:19], s[8:9]
	s_waitcnt vmcnt(17)
	v_sub_f32_e32 v144, v144, v198
	v_sub_f32_e32 v145, v145, v198
	v_sub_f32_e32 v146, v146, v198
	v_sub_f32_e32 v147, v147, v198
	v_mul_f32_e32 v144, v199, v144
	v_mul_f32_e32 v145, v199, v145
	v_mul_f32_e32 v146, v199, v146
	v_mul_f32_e32 v147, v199, v147
	v_fma_f32 v144, v144, v156, v172
	v_fma_f32 v145, v145, v157, v173
	v_fma_f32 v146, v146, v158, v174
	v_fma_f32 v147, v147, v159, v175
	v_fmac_f32_e32 v12, s30, v144
	v_fmac_f32_e32 v13, s30, v145
	v_fmac_f32_e32 v14, s30, v146
	v_fmac_f32_e32 v15, s30, v147
	v_add_u32_e32 v200, 0xb0000, v201
	global_store_dwordx4 v200, v[12:15], s[8:9] offset:16
	s_waitcnt vmcnt(16)
	v_sub_f32_e32 v204, v204, v198
	v_sub_f32_e32 v205, v205, v198
	v_sub_f32_e32 v206, v206, v198
	v_sub_f32_e32 v207, v207, v198
	v_mul_f32_e32 v204, v199, v204
	v_mul_f32_e32 v205, v199, v205
	v_mul_f32_e32 v206, v199, v206
	v_mul_f32_e32 v207, v199, v207
	v_fma_f32 v204, v204, v160, v176
	v_fma_f32 v205, v205, v161, v177
	v_fma_f32 v206, v206, v162, v178
	v_fma_f32 v207, v207, v163, v179
	v_fmac_f32_e32 v8, s30, v204
	v_fmac_f32_e32 v9, s30, v205
	v_fmac_f32_e32 v10, s30, v206
	v_fmac_f32_e32 v11, s30, v207
	v_add_u32_e32 v200, 0xb0000, v201
	global_store_dwordx4 v200, v[8:11], s[8:9] offset:512
	s_waitcnt vmcnt(15)
	v_sub_f32_e32 v208, v208, v198
	v_sub_f32_e32 v209, v209, v198
	v_sub_f32_e32 v210, v210, v198
	v_sub_f32_e32 v211, v211, v198
	v_mul_f32_e32 v208, v199, v208
	v_mul_f32_e32 v209, v199, v209
	v_mul_f32_e32 v210, v199, v210
	v_mul_f32_e32 v211, v199, v211
	v_fma_f32 v208, v208, v164, v180
	v_fma_f32 v209, v209, v165, v181
	v_fma_f32 v210, v210, v166, v182
	v_fma_f32 v211, v211, v167, v183
	v_fmac_f32_e32 v4, s30, v208
	v_fmac_f32_e32 v5, s30, v209
	v_fmac_f32_e32 v6, s30, v210
	v_fmac_f32_e32 v7, s30, v211
	v_add_u32_e32 v200, 0xb0000, v201
	global_store_dwordx4 v200, v[4:7], s[8:9] offset:528
	s_nop 1


	s_cbranch_vccnz .LBB0_677
	s_andn2_b64 vcc, exec, s[4:5]
	s_cbranch_vccnz .LBB0_676
	s_barrier
	s_branch .LBB0_676

.Llo_small:
	s_lshl_b32 s1, s86, 3
	s_add_i32 s0, s0, s1
	s_mul_i32 s0, s0, 0x2000
	s_add_u32 s4, s4, s0
	s_addc_u32 s5, s5, 0
	global_load_dwordx4 v[40:43], v1, s[4:5]
	global_load_dwordx4 v[44:47], v1, s[4:5] offset:1024
	global_load_dwordx4 v[48:51], v1, s[4:5] offset:2048
	global_load_dwordx4 v[52:55], v1, s[4:5] offset:3072
	global_load_dwordx4 v[8:11], v1, s[40:41]
	global_load_dwordx4 v[12:15], v1, s[40:41] offset:1024
	global_load_dwordx4 v[16:19], v1, s[40:41] offset:2048
	global_load_dwordx4 v[20:23], v1, s[40:41] offset:3072
	global_load_dwordx4 v[24:27], v1, s[42:43]
	global_load_dwordx4 v[28:31], v1, s[42:43] offset:1024
	global_load_dwordx4 v[32:35], v1, s[42:43] offset:2048
	global_load_dwordx4 v[36:39], v1, s[42:43] offset:3072
	v_add_u32_e32 v170, 0x1000, v1
	global_load_dwordx4 v[56:59], v170, s[4:5]
	global_load_dwordx4 v[60:63], v170, s[4:5] offset:1024
	global_load_dwordx4 v[64:67], v170, s[4:5] offset:2048
	global_load_dwordx4 v[68:71], v170, s[4:5] offset:3072
	s_waitcnt vmcnt(12)
	v_add_f32_e32 v180, v40, v41
	v_add_f32_e32 v181, v44, v45
	v_add_f32_e32 v182, v48, v49
	v_add_f32_e32 v183, v52, v53
	v_add_f32_e32 v180, v180, v42
	v_add_f32_e32 v181, v181, v46
	v_add_f32_e32 v182, v182, v50
	v_add_f32_e32 v183, v183, v54
	v_add_f32_e32 v180, v180, v43
	v_add_f32_e32 v181, v181, v47
	v_add_f32_e32 v182, v182, v51
	v_add_f32_e32 v183, v183, v55
	v_add_f32_e32 v180, v180, v181
	v_add_f32_e32 v182, v182, v183
	v_add_f32_e32 v180, v180, v182
	s_nop 1
	v_add_f32_dpp v180, v180, v180 quad_perm:[1,0,3,2] row_mask:0xf bank_mask:0xf
	s_nop 1
	v_add_f32_dpp v180, v180, v180 quad_perm:[2,3,0,1] row_mask:0xf bank_mask:0xf
	s_nop 1
	v_add_f32_dpp v180, v180, v180 row_half_mirror row_mask:0xf bank_mask:0xf
	s_nop 1
	v_add_f32_dpp v180, v180, v180 row_mirror row_mask:0xf bank_mask:0xf
	s_nop 1
	v_add_f32_dpp v180, v180, v180 row_bcast:15 row_mask:0xa bank_mask:0xf
	s_nop 1
	v_add_f32_dpp v180, v180, v180 row_bcast:31 row_mask:0xc bank_mask:0xf
	s_nop 0
	v_readlane_b32 s20, v180, 63
	s_nop 1
	v_mul_f32_e32 v184, s20, v2
	v_sub_f32_e32 v40, v40, v184
	v_sub_f32_e32 v41, v41, v184
	v_sub_f32_e32 v42, v42, v184
	v_sub_f32_e32 v43, v43, v184
	v_sub_f32_e32 v44, v44, v184
	v_sub_f32_e32 v45, v45, v184
	v_sub_f32_e32 v46, v46, v184
	v_sub_f32_e32 v47, v47, v184
	v_sub_f32_e32 v48, v48, v184
	v_sub_f32_e32 v49, v49, v184
	v_sub_f32_e32 v50, v50, v184
	v_sub_f32_e32 v51, v51, v184
	v_sub_f32_e32 v52, v52, v184
	v_sub_f32_e32 v53, v53, v184
	v_sub_f32_e32 v54, v54, v184
	v_sub_f32_e32 v55, v55, v184
	v_mul_f32_e32 v180, v40, v40
	v_mul_f32_e32 v181, v44, v44
	v_mul_f32_e32 v182, v48, v48
	v_mul_f32_e32 v183, v52, v52
	v_fmac_f32_e32 v180, v41, v41
	v_fmac_f32_e32 v181, v45, v45
	v_fmac_f32_e32 v182, v49, v49
	v_fmac_f32_e32 v183, v53, v53
	v_fmac_f32_e32 v180, v42, v42
	v_fmac_f32_e32 v181, v46, v46
	v_fmac_f32_e32 v182, v50, v50
	v_fmac_f32_e32 v183, v54, v54
	v_fmac_f32_e32 v180, v43, v43
	v_fmac_f32_e32 v181, v47, v47
	v_fmac_f32_e32 v182, v51, v51
	v_fmac_f32_e32 v183, v55, v55
	v_add_f32_e32 v180, v180, v181
	v_add_f32_e32 v182, v182, v183
	v_add_f32_e32 v180, v180, v182
	s_nop 1
	v_add_f32_dpp v180, v180, v180 quad_perm:[1,0,3,2] row_mask:0xf bank_mask:0xf
	s_nop 1
	v_add_f32_dpp v180, v180, v180 quad_perm:[2,3,0,1] row_mask:0xf bank_mask:0xf
	s_nop 1
	v_add_f32_dpp v180, v180, v180 row_half_mirror row_mask:0xf bank_mask:0xf
	s_nop 1
	v_add_f32_dpp v180, v180, v180 row_mirror row_mask:0xf bank_mask:0xf
	s_nop 1
	v_add_f32_dpp v180, v180, v180 row_bcast:15 row_mask:0xa bank_mask:0xf
	s_nop 1
	v_add_f32_dpp v180, v180, v180 row_bcast:31 row_mask:0xc bank_mask:0xf
	s_nop 0
	v_readlane_b32 s20, v180, 63
	s_nop 1
	v_mov_b32_e32 v185, s20
	v_fma_f32 v185, v185, v2, v4
	v_rsq_f32_e32 v185, v185
	s_nop 0
	v_mul_f32_e32 v40, v40, v185
	v_mul_f32_e32 v41, v41, v185
	v_mul_f32_e32 v42, v42, v185
	v_mul_f32_e32 v43, v43, v185
	v_mul_f32_e32 v44, v44, v185
	v_mul_f32_e32 v45, v45, v185
	v_mul_f32_e32 v46, v46, v185
	v_mul_f32_e32 v47, v47, v185
	v_mul_f32_e32 v48, v48, v185
	v_mul_f32_e32 v49, v49, v185
	v_mul_f32_e32 v50, v50, v185
	v_mul_f32_e32 v51, v51, v185
	v_mul_f32_e32 v52, v52, v185
	v_mul_f32_e32 v53, v53, v185
	v_mul_f32_e32 v54, v54, v185
	v_mul_f32_e32 v55, v55, v185
	s_waitcnt vmcnt(4)
	v_fma_f32 v40, v40, v8, v24
	v_fma_f32 v41, v41, v9, v25
	v_fma_f32 v42, v42, v10, v26
	v_fma_f32 v43, v43, v11, v27
	v_fma_f32 v44, v44, v12, v28
	v_fma_f32 v45, v45, v13, v29
	v_fma_f32 v46, v46, v14, v30
	v_fma_f32 v47, v47, v15, v31
	v_fma_f32 v48, v48, v16, v32
	v_fma_f32 v49, v49, v17, v33
	v_fma_f32 v50, v50, v18, v34
	v_fma_f32 v51, v51, v19, v35
	v_fma_f32 v52, v52, v20, v36
	v_fma_f32 v53, v53, v21, v37
	v_fma_f32 v54, v54, v22, v38
	v_fma_f32 v55, v55, v23, v39
	global_store_dwordx4 v1, v[40:43], s[4:5]
	global_store_dwordx4 v1, v[44:47], s[4:5] offset:1024
	global_store_dwordx4 v1, v[48:51], s[4:5] offset:2048
	global_store_dwordx4 v1, v[52:55], s[4:5] offset:3072
	s_waitcnt vmcnt(4)
	v_add_f32_e32 v180, v56, v57
	v_add_f32_e32 v181, v60, v61
	v_add_f32_e32 v182, v64, v65
	v_add_f32_e32 v183, v68, v69
	v_add_f32_e32 v180, v180, v58
	v_add_f32_e32 v181, v181, v62
	v_add_f32_e32 v182, v182, v66
	v_add_f32_e32 v183, v183, v70
	v_add_f32_e32 v180, v180, v59
	v_add_f32_e32 v181, v181, v63
	v_add_f32_e32 v182, v182, v67
	v_add_f32_e32 v183, v183, v71
	v_add_f32_e32 v180, v180, v181
	v_add_f32_e32 v182, v182, v183
	v_add_f32_e32 v180, v180, v182
	s_nop 1
	v_add_f32_dpp v180, v180, v180 quad_perm:[1,0,3,2] row_mask:0xf bank_mask:0xf
	s_nop 1
	v_add_f32_dpp v180, v180, v180 quad_perm:[2,3,0,1] row_mask:0xf bank_mask:0xf
	s_nop 1
	v_add_f32_dpp v180, v180, v180 row_half_mirror row_mask:0xf bank_mask:0xf
	s_nop 1
	v_add_f32_dpp v180, v180, v180 row_mirror row_mask:0xf bank_mask:0xf
	s_nop 1
	v_add_f32_dpp v180, v180, v180 row_bcast:15 row_mask:0xa bank_mask:0xf
	s_nop 1
	v_add_f32_dpp v180, v180, v180 row_bcast:31 row_mask:0xc bank_mask:0xf
	s_nop 0
	v_readlane_b32 s20, v180, 63
	s_nop 1
	v_mul_f32_e32 v184, s20, v2
	v_sub_f32_e32 v56, v56, v184
	v_sub_f32_e32 v57, v57, v184
	v_sub_f32_e32 v58, v58, v184
	v_sub_f32_e32 v59, v59, v184
	v_sub_f32_e32 v60, v60, v184
	v_sub_f32_e32 v61, v61, v184
	v_sub_f32_e32 v62, v62, v184
	v_sub_f32_e32 v63, v63, v184
	v_sub_f32_e32 v64, v64, v184
	v_sub_f32_e32 v65, v65, v184
	v_sub_f32_e32 v66, v66, v184
	v_sub_f32_e32 v67, v67, v184
	v_sub_f32_e32 v68, v68, v184
	v_sub_f32_e32 v69, v69, v184
	v_sub_f32_e32 v70, v70, v184
	v_sub_f32_e32 v71, v71, v184
	v_mul_f32_e32 v180, v56, v56
	v_mul_f32_e32 v181, v60, v60
	v_mul_f32_e32 v182, v64, v64
	v_mul_f32_e32 v183, v68, v68
	v_fmac_f32_e32 v180, v57, v57
	v_fmac_f32_e32 v181, v61, v61
	v_fmac_f32_e32 v182, v65, v65
	v_fmac_f32_e32 v183, v69, v69
	v_fmac_f32_e32 v180, v58, v58
	v_fmac_f32_e32 v181, v62, v62
	v_fmac_f32_e32 v182, v66, v66
	v_fmac_f32_e32 v183, v70, v70
	v_fmac_f32_e32 v180, v59, v59
	v_fmac_f32_e32 v181, v63, v63
	v_fmac_f32_e32 v182, v67, v67
	v_fmac_f32_e32 v183, v71, v71
	v_add_f32_e32 v180, v180, v181
	v_add_f32_e32 v182, v182, v183
	v_add_f32_e32 v180, v180, v182
	s_nop 1
	v_add_f32_dpp v180, v180, v180 quad_perm:[1,0,3,2] row_mask:0xf bank_mask:0xf
	s_nop 1
	v_add_f32_dpp v180, v180, v180 quad_perm:[2,3,0,1] row_mask:0xf bank_mask:0xf
	s_nop 1
	v_add_f32_dpp v180, v180, v180 row_half_mirror row_mask:0xf bank_mask:0xf
	s_nop 1
	v_add_f32_dpp v180, v180, v180 row_mirror row_mask:0xf bank_mask:0xf
	s_nop 1
	v_add_f32_dpp v180, v180, v180 row_bcast:15 row_mask:0xa bank_mask:0xf
	s_nop 1
	v_add_f32_dpp v180, v180, v180 row_bcast:31 row_mask:0xc bank_mask:0xf
	s_nop 0
	v_readlane_b32 s20, v180, 63
	s_nop 1
	v_mov_b32_e32 v185, s20
	v_fma_f32 v185, v185, v2, v4
	v_rsq_f32_e32 v185, v185
	s_nop 0
	v_mul_f32_e32 v56, v56, v185
	v_mul_f32_e32 v57, v57, v185
	v_mul_f32_e32 v58, v58, v185
	v_mul_f32_e32 v59, v59, v185
	v_mul_f32_e32 v60, v60, v185
	v_mul_f32_e32 v61, v61, v185
	v_mul_f32_e32 v62, v62, v185
	v_mul_f32_e32 v63, v63, v185
	v_mul_f32_e32 v64, v64, v185
	v_mul_f32_e32 v65, v65, v185
	v_mul_f32_e32 v66, v66, v185
	v_mul_f32_e32 v67, v67, v185
	v_mul_f32_e32 v68, v68, v185
	v_mul_f32_e32 v69, v69, v185
	v_mul_f32_e32 v70, v70, v185
	v_mul_f32_e32 v71, v71, v185
	v_fma_f32 v56, v56, v8, v24
	v_fma_f32 v57, v57, v9, v25
	v_fma_f32 v58, v58, v10, v26
	v_fma_f32 v59, v59, v11, v27
	v_fma_f32 v60, v60, v12, v28
	v_fma_f32 v61, v61, v13, v29
	v_fma_f32 v62, v62, v14, v30
	v_fma_f32 v63, v63, v15, v31
	v_fma_f32 v64, v64, v16, v32
	v_fma_f32 v65, v65, v17, v33
	v_fma_f32 v66, v66, v18, v34
	v_fma_f32 v67, v67, v19, v35
	v_fma_f32 v68, v68, v20, v36
	v_fma_f32 v69, v69, v21, v37
	v_fma_f32 v70, v70, v22, v38
	v_fma_f32 v71, v71, v23, v39
	v_add_u32_e32 v171, 0x1000, v1
	global_store_dwordx4 v171, v[56:59], s[4:5]
	global_store_dwordx4 v171, v[60:63], s[4:5] offset:1024
	global_store_dwordx4 v171, v[64:67], s[4:5] offset:2048
	global_store_dwordx4 v171, v[68:71], s[4:5] offset:3072
	s_branch .Ltr_29
